# v67 (group-7 deferral + group-0 hoist) + the six K-loop heads aligned to 64 bytes
# baseline (speedup 1.0000x reference)
.Lmy_up_join:
	s_waitcnt lgkmcnt(0)
	s_barrier
	s_setprio 1
	s_waitcnt lgkmcnt(0)
	v_mfma_f32_16x16x32_bf16 v[60:63], v[138:141], v[210:213], 0
	v_mfma_f32_16x16x32_bf16 v[52:55], v[176:179], v[210:213], 0
	v_mfma_f32_16x16x32_bf16 v[44:47], v[138:141], v[218:221], 0
	v_mfma_f32_16x16x32_bf16 v[36:39], v[176:179], v[218:221], 0
	v_mfma_f32_16x16x32_bf16 v[28:31], v[138:141], v[228:231], 0
	v_mfma_f32_16x16x32_bf16 v[20:23], v[176:179], v[228:231], 0
	v_mfma_f32_16x16x32_bf16 v[12:15], v[138:141], v[236:239], 0
	v_mfma_f32_16x16x32_bf16 v[4:7], v[176:179], v[236:239], 0
	v_mfma_f32_16x16x32_bf16 v[60:63], v[172:175], v[214:217], v[60:63]
	v_mfma_f32_16x16x32_bf16 v[52:55], v[180:183], v[214:217], v[52:55]
	v_mfma_f32_16x16x32_bf16 v[44:47], v[172:175], v[224:227], v[44:47]
	v_mfma_f32_16x16x32_bf16 v[36:39], v[180:183], v[224:227], v[36:39]
	v_mfma_f32_16x16x32_bf16 v[28:31], v[172:175], v[232:235], v[28:31]
	v_mfma_f32_16x16x32_bf16 v[20:23], v[180:183], v[232:235], v[20:23]
	v_mfma_f32_16x16x32_bf16 v[12:15], v[172:175], v[240:243], v[12:15]
	v_mfma_f32_16x16x32_bf16 v[4:7], v[180:183], v[240:243], v[4:7]
	s_setprio 0
	s_setprio 1
	v_mfma_f32_16x16x32_bf16 v[56:59], v[184:187], v[210:213], 0
	v_mfma_f32_16x16x32_bf16 v[48:51], v[192:195], v[210:213], 0
	v_mfma_f32_16x16x32_bf16 v[40:43], v[184:187], v[218:221], 0
	v_mfma_f32_16x16x32_bf16 v[32:35], v[192:195], v[218:221], 0
	v_mfma_f32_16x16x32_bf16 v[24:27], v[184:187], v[228:231], 0
	v_mfma_f32_16x16x32_bf16 v[16:19], v[192:195], v[228:231], 0
	v_mfma_f32_16x16x32_bf16 v[8:11], v[184:187], v[236:239], 0
	v_mfma_f32_16x16x32_bf16 v[0:3], v[192:195], v[236:239], 0
	v_mfma_f32_16x16x32_bf16 v[56:59], v[188:191], v[214:217], v[56:59]
	v_mfma_f32_16x16x32_bf16 v[48:51], v[196:199], v[214:217], v[48:51]
	v_mfma_f32_16x16x32_bf16 v[40:43], v[188:191], v[224:227], v[40:43]
	v_mfma_f32_16x16x32_bf16 v[32:35], v[196:199], v[224:227], v[32:35]
	v_mfma_f32_16x16x32_bf16 v[24:27], v[188:191], v[232:235], v[24:27]
	v_mfma_f32_16x16x32_bf16 v[16:19], v[196:199], v[232:235], v[16:19]
	v_mfma_f32_16x16x32_bf16 v[8:11], v[188:191], v[240:243], v[8:11]
	v_mfma_f32_16x16x32_bf16 v[0:3], v[196:199], v[240:243], v[0:3]
	s_setprio 0
	s_barrier
	s_add_i32 s92, 0, 0x18000
	v_add_u32_e32 v149, s92, v145
	s_add_i32 s93, 0, 0x1c000
	ds_read_b128 v[138:141], v149
	ds_read_b128 v[172:175], v149 offset:1024
	ds_read_b128 v[176:179], v149 offset:2048
	ds_read_b128 v[180:183], v149 offset:3072
	v_add_u32_e32 v149, s93, v145
	ds_read_b128 v[184:187], v149
	ds_read_b128 v[188:191], v149 offset:1024
	ds_read_b128 v[192:195], v149 offset:2048
	ds_read_b128 v[196:199], v149 offset:3072
	s_add_u32 s86, vcc_lo, 0x40000
	s_addc_u32 s87, vcc_hi, 0
	s_mov_b32 m0, s74
	v_lshl_add_u64 v[248:249], s[86:87], 0, v[132:133]
	ds_read_b128 v[210:213], v148 offset:32768
	ds_read_b128 v[214:217], v148 offset:33792
	ds_read_b128 v[218:221], v148 offset:34816
	ds_read_b128 v[224:227], v148 offset:35840
	ds_read_b128 v[228:231], v148 offset:36864
	ds_read_b128 v[232:235], v148 offset:37888
	ds_read_b128 v[236:239], v148 offset:38912
	ds_read_b128 v[240:243], v148 offset:39936
	global_load_lds_dwordx4 v[248:249], off
	v_lshl_add_u64 v[248:249], s[86:87], 0, v[130:131]
	s_mov_b32 m0, s75
	s_nop 0
	global_load_lds_dwordx4 v[248:249], off
	s_waitcnt vmcnt(8)
	s_waitcnt lgkmcnt(0)
	s_barrier
	s_setprio 1
	s_waitcnt lgkmcnt(0)
	v_mfma_f32_16x16x32_bf16 v[124:127], v[138:141], v[210:213], v[124:127]
	v_mfma_f32_16x16x32_bf16 v[116:119], v[176:179], v[210:213], v[116:119]
	v_mfma_f32_16x16x32_bf16 v[108:111], v[138:141], v[218:221], v[108:111]
	v_mfma_f32_16x16x32_bf16 v[100:103], v[176:179], v[218:221], v[100:103]
	v_mfma_f32_16x16x32_bf16 v[92:95], v[138:141], v[228:231], v[92:95]
	v_mfma_f32_16x16x32_bf16 v[84:87], v[176:179], v[228:231], v[84:87]
	v_mfma_f32_16x16x32_bf16 v[76:79], v[138:141], v[236:239], v[76:79]
	v_mfma_f32_16x16x32_bf16 v[68:71], v[176:179], v[236:239], v[68:71]
	v_mfma_f32_16x16x32_bf16 v[124:127], v[172:175], v[214:217], v[124:127]
	v_mfma_f32_16x16x32_bf16 v[116:119], v[180:183], v[214:217], v[116:119]
	v_mfma_f32_16x16x32_bf16 v[108:111], v[172:175], v[224:227], v[108:111]
	v_mfma_f32_16x16x32_bf16 v[100:103], v[180:183], v[224:227], v[100:103]
	v_mfma_f32_16x16x32_bf16 v[92:95], v[172:175], v[232:235], v[92:95]
	v_mfma_f32_16x16x32_bf16 v[84:87], v[180:183], v[232:235], v[84:87]
	v_mfma_f32_16x16x32_bf16 v[76:79], v[172:175], v[240:243], v[76:79]
	v_mfma_f32_16x16x32_bf16 v[68:71], v[180:183], v[240:243], v[68:71]
	s_setprio 0
	s_setprio 1
	v_mfma_f32_16x16x32_bf16 v[120:123], v[184:187], v[210:213], v[120:123]
	v_mfma_f32_16x16x32_bf16 v[112:115], v[192:195], v[210:213], v[112:115]
	v_mfma_f32_16x16x32_bf16 v[104:107], v[184:187], v[218:221], v[104:107]
	v_mfma_f32_16x16x32_bf16 v[96:99], v[192:195], v[218:221], v[96:99]
	v_mfma_f32_16x16x32_bf16 v[88:91], v[184:187], v[228:231], v[88:91]
	v_mfma_f32_16x16x32_bf16 v[80:83], v[192:195], v[228:231], v[80:83]
	v_mfma_f32_16x16x32_bf16 v[72:75], v[184:187], v[236:239], v[72:75]
	v_mfma_f32_16x16x32_bf16 v[64:67], v[192:195], v[236:239], v[64:67]
	v_mfma_f32_16x16x32_bf16 v[120:123], v[188:191], v[214:217], v[120:123]
	v_mfma_f32_16x16x32_bf16 v[112:115], v[196:199], v[214:217], v[112:115]
	v_mfma_f32_16x16x32_bf16 v[104:107], v[188:191], v[224:227], v[104:107]
	v_mfma_f32_16x16x32_bf16 v[96:99], v[196:199], v[224:227], v[96:99]
	v_mfma_f32_16x16x32_bf16 v[88:91], v[188:191], v[232:235], v[88:91]
	v_mfma_f32_16x16x32_bf16 v[80:83], v[196:199], v[232:235], v[80:83]
	v_mfma_f32_16x16x32_bf16 v[72:75], v[188:191], v[240:243], v[72:75]
	v_mfma_f32_16x16x32_bf16 v[64:67], v[196:199], v[240:243], v[64:67]
	s_setprio 0
	s_barrier
	s_add_i32 s86, s92, s67
	v_lshl_add_u64 v[142:143], v[142:143], 0, s[22:23]
	s_mov_b32 m0, s86
	ds_read_b128 v[210:213], v148 offset:49152
	ds_read_b128 v[214:217], v148 offset:50176
	ds_read_b128 v[218:221], v148 offset:51200
	ds_read_b128 v[224:227], v148 offset:52224
	ds_read_b128 v[228:231], v148 offset:53248
	ds_read_b128 v[232:235], v148 offset:54272
	ds_read_b128 v[236:239], v148 offset:55296
	ds_read_b128 v[240:243], v148 offset:56320
	global_load_lds_dwordx4 v[142:143], off
	s_add_i32 m0, s86, 0x2000
	s_add_u32 s62, s62, 0x40080
	v_lshl_add_u64 v[142:143], v[150:151], 0, s[22:23]
	s_addc_u32 s63, s63, 0
	s_add_i32 s86, s93, s67
	global_load_lds_dwordx4 v[142:143], off
	v_lshl_add_u64 v[142:143], s[62:63], 0, v[152:153]
	s_mov_b32 m0, s86
	s_nop 0
	global_load_lds_dwordx4 v[142:143], off
	v_lshl_add_u64 v[142:143], s[62:63], 0, v[128:129]
	s_add_i32 m0, s86, 0x2000
	s_nop 0
	global_load_lds_dwordx4 v[142:143], off
	v_lshl_add_u64 v[142:143], v[244:245], 0, s[22:23]
	s_mov_b32 m0, s77
	s_nop 0
	global_load_lds_dwordx4 v[142:143], off
	v_lshl_add_u64 v[142:143], v[246:247], 0, s[22:23]
	s_mov_b32 m0, s78
	s_nop 0
	global_load_lds_dwordx4 v[142:143], off
	s_waitcnt vmcnt(8)
	s_waitcnt lgkmcnt(0)
	s_barrier
	s_setprio 1
	s_waitcnt lgkmcnt(0)
	v_mfma_f32_16x16x32_bf16 v[60:63], v[138:141], v[210:213], v[60:63]
	v_mfma_f32_16x16x32_bf16 v[52:55], v[176:179], v[210:213], v[52:55]
	v_mfma_f32_16x16x32_bf16 v[44:47], v[138:141], v[218:221], v[44:47]
	v_mfma_f32_16x16x32_bf16 v[36:39], v[176:179], v[218:221], v[36:39]
	v_mfma_f32_16x16x32_bf16 v[28:31], v[138:141], v[228:231], v[28:31]
	v_mfma_f32_16x16x32_bf16 v[20:23], v[176:179], v[228:231], v[20:23]
	v_mfma_f32_16x16x32_bf16 v[12:15], v[138:141], v[236:239], v[12:15]
	v_mfma_f32_16x16x32_bf16 v[4:7], v[176:179], v[236:239], v[4:7]
	v_mfma_f32_16x16x32_bf16 v[60:63], v[172:175], v[214:217], v[60:63]
	v_mfma_f32_16x16x32_bf16 v[52:55], v[180:183], v[214:217], v[52:55]
	v_mfma_f32_16x16x32_bf16 v[44:47], v[172:175], v[224:227], v[44:47]
	v_mfma_f32_16x16x32_bf16 v[36:39], v[180:183], v[224:227], v[36:39]
	v_mfma_f32_16x16x32_bf16 v[28:31], v[172:175], v[232:235], v[28:31]
	v_mfma_f32_16x16x32_bf16 v[20:23], v[180:183], v[232:235], v[20:23]
	v_mfma_f32_16x16x32_bf16 v[12:15], v[172:175], v[240:243], v[12:15]
	v_mfma_f32_16x16x32_bf16 v[4:7], v[180:183], v[240:243], v[4:7]
	s_setprio 0
	s_setprio 1
	v_mfma_f32_16x16x32_bf16 v[56:59], v[184:187], v[210:213], v[56:59]
	v_mfma_f32_16x16x32_bf16 v[48:51], v[192:195], v[210:213], v[48:51]
	v_mfma_f32_16x16x32_bf16 v[40:43], v[184:187], v[218:221], v[40:43]
	v_mfma_f32_16x16x32_bf16 v[32:35], v[192:195], v[218:221], v[32:35]
	v_mfma_f32_16x16x32_bf16 v[24:27], v[184:187], v[228:231], v[24:27]
	v_mfma_f32_16x16x32_bf16 v[16:19], v[192:195], v[228:231], v[16:19]
	v_mfma_f32_16x16x32_bf16 v[8:11], v[184:187], v[236:239], v[8:11]
	v_mfma_f32_16x16x32_bf16 v[0:3], v[192:195], v[236:239], v[0:3]
	v_mfma_f32_16x16x32_bf16 v[56:59], v[188:191], v[214:217], v[56:59]
	v_mfma_f32_16x16x32_bf16 v[48:51], v[196:199], v[214:217], v[48:51]
	v_mfma_f32_16x16x32_bf16 v[40:43], v[188:191], v[224:227], v[40:43]
	v_mfma_f32_16x16x32_bf16 v[32:35], v[196:199], v[224:227], v[32:35]
	v_mfma_f32_16x16x32_bf16 v[24:27], v[188:191], v[232:235], v[24:27]
	v_mfma_f32_16x16x32_bf16 v[16:19], v[196:199], v[232:235], v[16:19]
	v_mfma_f32_16x16x32_bf16 v[8:11], v[188:191], v[240:243], v[8:11]
	v_mfma_f32_16x16x32_bf16 v[0:3], v[196:199], v[240:243], v[0:3]
	s_setprio 0
	s_barrier
	s_add_i32 s85, s85, 2
	s_add_u32 s89, s89, 0x100
	s_addc_u32 s84, s84, 0
	s_add_u32 s60, s60, 0x100
	s_addc_u32 s61, s61, 0
	s_cmp_gt_u32 s85, 13
	.p2align	6
